# v6 + group barrier (32 workgroups sharing bx&7) instead of the grid barrier at G7->G8, D6U->D6D and D6D(0)->D6U(1)
# speedup vs baseline: 1.0123x; 1.0003x over previous
.LBB0_992:
	s_andn2_b64 vcc, exec, s[0:1]
	s_cbranch_vccnz .LBB0_1046
	s_waitcnt vmcnt(0)
	s_waitcnt vmcnt(0)
	s_barrier
	s_mov_b64 s[36:37], exec
	v_readlane_b32 s6, v253, 27
	v_readlane_b32 s7, v253, 28
	s_and_b64 s[6:7], s[36:37], s[6:7]
	s_mov_b64 exec, s[6:7]
	s_cbranch_execz .LBB0_1045
	s_cmpk_lg_u32 s33, 0x100
	s_cbranch_scc1 Lxg_g7_full
	buffer_wbl2 sc1
	v_readlane_b32 s6, v253, 7
	v_readlane_b32 s7, v253, 8
	v_readlane_b32 s8, v253, 4
	v_mov_b32_e32 v4, 0
	v_mov_b32_e32 v2, 1
	s_lshr_b32 s8, s8, 5
	s_lshl_b32 s8, s8, 8
	s_add_u32 s6, s6, s8
	s_addc_u32 s7, s7, 0
	s_add_u32 s6, s6, 0xc0000
	s_addc_u32 s7, s7, 0
	s_waitcnt vmcnt(0) lgkmcnt(0)
	global_atomic_add v3, v4, v2, s[6:7] sc0
	s_mov_b32 s9, 0
	s_waitcnt vmcnt(0)
	v_or_b32_e32 v3, 31, v3
Lxg_g7_spin:
	global_load_dword v2, v4, s[6:7] sc1
	s_add_i32 s9, s9, 1
	s_waitcnt vmcnt(0)
	v_cmp_gt_u32_e32 vcc, v2, v3
	s_cbranch_vccnz Lxg_g7_done
	s_sleep 1
	s_cmp_lt_u32 s9, 0x40000
	s_cbranch_scc1 Lxg_g7_spin
Lxg_g7_done:
	buffer_inv sc1
	s_waitcnt vmcnt(0)
	s_branch .LBB0_1045
Lxg_g7_full:
	v_mov_b32_e32 v2, s87
	s_waitcnt vmcnt(0) expcnt(0) lgkmcnt(0)
	ds_read_b32 v4, v2
	v_mov_b32_e32 v2, s39
	ds_read_b32 v2, v2
	s_waitcnt lgkmcnt(1)
	v_cmp_ne_u32_e32 vcc, 0, v4
	s_cbranch_vccnz .LBB0_1009
	v_readlane_b32 s8, v253, 0
	v_readlane_b32 s9, v253, 1
	s_load_dwordx2 s[6:7], s[8:9], 0x4
	s_waitcnt lgkmcnt(0)
	s_mul_i32 s5, s6, s33
	s_mul_i32 s5, s5, s7
	s_mov_b32 s6, 1
	s_branch .LBB0_997

.LBB0_1591:
	s_mov_b32 s98, s5
	s_lshl_b32 s40, s5, 14
	s_lshl_b32 s5, s5, 1
	s_add_i32 s6, s44, s5
	s_cmp_le_i32 s94, s6
	s_cselect_b64 s[8:9], -1, 0
	s_cmp_lt_i32 s6, s95
	s_cselect_b64 s[10:11], -1, 0
	s_and_b64 s[8:9], s[8:9], s[10:11]
	s_andn2_b64 vcc, exec, s[8:9]
	s_cbranch_vccnz .LBB0_1670
	v_readlane_b32 s8, v253, 5
	v_readlane_b32 s9, v253, 6
	v_readlane_b32 s10, v253, 7
	v_readlane_b32 s11, v253, 8
	v_mov_b32_e32 v2, v1
	s_mov_b64 s[36:37], s[10:11]
	s_mov_b32 s7, s50
	v_readlane_b32 s8, v253, 4
	v_readlane_b32 s9, v253, 29
	v_mov_b32_e32 v16, v0
	s_cmpk_gt_i32 s7, 0x7ff
	v_readfirstlane_b32 s20, v16
	s_cbranch_scc1 .LBB0_1616
	s_ashr_i32 s8, s7, 31
	s_lshr_b32 s9, s8, 29
	s_add_i32 s10, s7, s9
	s_and_b32 s9, s10, -8
	s_sub_i32 s9, s7, s9
	s_cmp_gt_i32 s9, -1
	s_mov_b64 s[38:39], -1
	s_cbranch_scc0 .LBB0_1595
	s_lshl_b32 s14, s9, 8
	s_mov_b64 s[38:39], 0

.LBB0_1616:
	s_or_b32 s6, s6, 1
	s_cmp_ge_i32 s6, s95
	s_cbranch_scc1 .LBB0_1670
	s_waitcnt vmcnt(0)
	s_waitcnt vmcnt(0)
	s_barrier
	s_mov_b64 s[36:37], exec
	v_readlane_b32 s6, v253, 27
	v_readlane_b32 s7, v253, 28
	s_and_b64 s[6:7], s[36:37], s[6:7]
	s_mov_b64 exec, s[6:7]
	s_cbranch_execz .LBB0_1669
	s_cmpk_lg_u32 s33, 0x100
	s_cbranch_scc1 Lxg_d6u_full
	buffer_wbl2 sc1
	v_readlane_b32 s6, v253, 7
	v_readlane_b32 s7, v253, 8
	v_readlane_b32 s8, v253, 4
	v_mov_b32_e32 v4, 0
	v_mov_b32_e32 v2, 1
	s_lshr_b32 s8, s8, 5
	s_lshl_b32 s8, s8, 8
	s_add_u32 s6, s6, s8
	s_addc_u32 s7, s7, 0
	s_add_u32 s6, s6, 0xc0000
	s_addc_u32 s7, s7, 0
	s_waitcnt vmcnt(0) lgkmcnt(0)
	global_atomic_add v3, v4, v2, s[6:7] sc0
	s_mov_b32 s9, 0
	s_waitcnt vmcnt(0)
	v_or_b32_e32 v3, 31, v3
Lxg_d6u_spin:
	global_load_dword v2, v4, s[6:7] sc1
	s_add_i32 s9, s9, 1
	s_waitcnt vmcnt(0)
	v_cmp_gt_u32_e32 vcc, v2, v3
	s_cbranch_vccnz Lxg_d6u_done
	s_sleep 1
	s_cmp_lt_u32 s9, 0x40000
	s_cbranch_scc1 Lxg_d6u_spin
Lxg_d6u_done:
	buffer_inv sc1
	s_waitcnt vmcnt(0)
	s_branch .LBB0_1669
Lxg_d6u_full:
	v_readlane_b32 s6, v255, 8
	s_waitcnt vmcnt(0) expcnt(0) lgkmcnt(0)
	s_nop 0
	v_mov_b32_e32 v2, s6
	ds_read_b32 v4, v2
	v_readlane_b32 s6, v255, 9
	s_waitcnt lgkmcnt(0)
	v_cmp_ne_u32_e32 vcc, 0, v4
	v_mov_b32_e32 v2, s6
	ds_read_b32 v2, v2
	s_cbranch_vccnz .LBB0_1633
	v_readlane_b32 s8, v253, 0
	v_readlane_b32 s9, v253, 1
	s_load_dwordx2 s[6:7], s[8:9], 0x4
	s_waitcnt lgkmcnt(0)
	s_mul_i32 s6, s6, s33
	s_mul_i32 s6, s6, s7
	s_mov_b32 s7, 1
	s_branch .LBB0_1621

.LBB0_1695:
	s_add_i32 s5, s5, 1
	s_cmp_ge_i32 s5, s95
	s_cbranch_scc1 .LBB0_1590
	s_waitcnt vmcnt(0)
	s_waitcnt vmcnt(0)
	s_barrier
	s_mov_b64 s[36:37], exec
	v_readlane_b32 s6, v253, 27
	v_readlane_b32 s7, v253, 28
	s_and_b64 s[6:7], s[36:37], s[6:7]
	s_mov_b64 exec, s[6:7]
	s_cbranch_execz .LBB0_1589
	s_cmpk_lg_u32 s33, 0x100
	s_cbranch_scc1 Lxg_d6d_full
	s_cmp_lg_u32 s98, 0
	s_cbranch_scc1 Lxg_d6d_full
	buffer_wbl2 sc1
	v_readlane_b32 s6, v253, 7
	v_readlane_b32 s7, v253, 8
	v_readlane_b32 s8, v253, 4
	v_mov_b32_e32 v4, 0
	v_mov_b32_e32 v2, 1
	s_lshr_b32 s8, s8, 5
	s_lshl_b32 s8, s8, 8
	s_add_u32 s6, s6, s8
	s_addc_u32 s7, s7, 0
	s_add_u32 s6, s6, 0xc0000
	s_addc_u32 s7, s7, 0
	s_waitcnt vmcnt(0) lgkmcnt(0)
	global_atomic_add v3, v4, v2, s[6:7] sc0
	s_mov_b32 s9, 0
	s_waitcnt vmcnt(0)
	v_or_b32_e32 v3, 31, v3
Lxg_d6d_spin:
	global_load_dword v2, v4, s[6:7] sc1
	s_add_i32 s9, s9, 1
	s_waitcnt vmcnt(0)
	v_cmp_gt_u32_e32 vcc, v2, v3
	s_cbranch_vccnz Lxg_d6d_done
	s_sleep 1
	s_cmp_lt_u32 s9, 0x40000
	s_cbranch_scc1 Lxg_d6d_spin
Lxg_d6d_done:
	buffer_inv sc1
	s_waitcnt vmcnt(0)
	s_branch .LBB0_1589
Lxg_d6d_full:
	v_readlane_b32 s5, v255, 8
	s_waitcnt vmcnt(0) expcnt(0) lgkmcnt(0)
	s_nop 0
	v_mov_b32_e32 v2, s5
	ds_read_b32 v4, v2
	v_readlane_b32 s5, v255, 9
	s_waitcnt lgkmcnt(0)
	v_cmp_ne_u32_e32 vcc, 0, v4
	v_mov_b32_e32 v2, s5
	ds_read_b32 v2, v2
	s_cbranch_vccnz .LBB0_1712
	v_readlane_b32 s8, v253, 0
	v_readlane_b32 s9, v253, 1
	s_load_dwordx2 s[6:7], s[8:9], 0x4
	s_waitcnt lgkmcnt(0)
	s_mul_i32 s5, s6, s33
	s_mul_i32 s5, s5, s7
	s_mov_b32 s6, 1
	s_branch .LBB0_1700

	.amdhsa_kernel _Z8yoco_fwd4Args
		.amdhsa_group_segment_fixed_size 0
		.amdhsa_private_segment_fixed_size 0
		.amdhsa_kernarg_size 408
		.amdhsa_user_sgpr_count 2
		.amdhsa_user_sgpr_dispatch_ptr 0
		.amdhsa_user_sgpr_queue_ptr 0
		.amdhsa_user_sgpr_kernarg_segment_ptr 1
		.amdhsa_user_sgpr_dispatch_id 0
		.amdhsa_user_sgpr_kernarg_preload_length 0
		.amdhsa_user_sgpr_kernarg_preload_offset 0
		.amdhsa_user_sgpr_private_segment_size 0
		.amdhsa_uses_dynamic_stack 0
		.amdhsa_enable_private_segment 0
		.amdhsa_system_sgpr_workgroup_id_x 1
		.amdhsa_system_sgpr_workgroup_id_y 0
		.amdhsa_system_sgpr_workgroup_id_z 0
		.amdhsa_system_sgpr_workgroup_info 0
		.amdhsa_system_vgpr_workitem_id 0
		.amdhsa_next_free_vgpr 256
		.amdhsa_next_free_sgpr 102
		.amdhsa_accum_offset 256
		.amdhsa_reserve_vcc 1
		.amdhsa_float_round_mode_32 0
		.amdhsa_float_round_mode_16_64 0
		.amdhsa_float_denorm_mode_32 3
		.amdhsa_float_denorm_mode_16_64 3
		.amdhsa_dx10_clamp 1
		.amdhsa_ieee_mode 1
		.amdhsa_fp16_overflow 0
		.amdhsa_tg_split 0
		.amdhsa_exception_fp_ieee_invalid_op 0
		.amdhsa_exception_fp_denorm_src 0
		.amdhsa_exception_fp_ieee_div_zero 0
		.amdhsa_exception_fp_ieee_overflow 0
		.amdhsa_exception_fp_ieee_underflow 0
		.amdhsa_exception_fp_ieee_inexact 0
		.amdhsa_exception_int_div_zero 0
	.end_amdhsa_kernel

amdhsa.kernels:
  - .agpr_count:     0
    .args:
      - .offset:         0
        .size:           152
        .value_kind:     by_value
      - .offset:         152
        .size:           4
        .value_kind:     hidden_block_count_x
      - .offset:         156
        .size:           4
        .value_kind:     hidden_block_count_y
      - .offset:         160
        .size:           4
        .value_kind:     hidden_block_count_z
      - .offset:         164
        .size:           2
        .value_kind:     hidden_group_size_x
      - .offset:         166
        .size:           2
        .value_kind:     hidden_group_size_y
      - .offset:         168
        .size:           2
        .value_kind:     hidden_group_size_z
      - .offset:         170
        .size:           2
        .value_kind:     hidden_remainder_x
      - .offset:         172
        .size:           2
        .value_kind:     hidden_remainder_y
      - .offset:         174
        .size:           2
        .value_kind:     hidden_remainder_z
      - .offset:         192
        .size:           8
        .value_kind:     hidden_global_offset_x
      - .offset:         200
        .size:           8
        .value_kind:     hidden_global_offset_y
      - .offset:         208
        .size:           8
        .value_kind:     hidden_global_offset_z
      - .offset:         216
        .size:           2
        .value_kind:     hidden_grid_dims
      - .offset:         272
        .size:           4
        .value_kind:     hidden_dynamic_lds_size
    .group_segment_fixed_size: 0
    .kernarg_segment_align: 8
    .kernarg_segment_size: 408
    .language:       OpenCL C
    .language_version:
      - 2
      - 0
    .max_flat_workgroup_size: 512
    .name:           _Z8yoco_fwd4Args
    .private_segment_fixed_size: 0
    .sgpr_count:     108
    .sgpr_spill_count: 164
    .symbol:         _Z8yoco_fwd4Args.kd
    .uniform_work_group_size: 1
    .uses_dynamic_stack: false
    .vgpr_count:     256
    .vgpr_spill_count: 0
    .wavefront_size: 64
